# ctx attention (MODE 0/1, no masking): dead per-element score guard (v_cmp + v_cndmask, 64 VALU ops per tile) removed
# baseline (speedup 1.0000x reference)
.LBB0_239:
	s_barrier
	ds_write_b128 v104, v[44:47]
	ds_write_b128 v106, v[40:43]
	v_and_b32_e32 v223, 0xff, v160
	v_lshrrev_b32_e32 v224, 2, v223
	v_and_b32_e32 v225, 3, v223
	v_lshrrev_b32_e32 v226, 1, v225
	v_bfe_u32 v227, v224, 1, 1
	v_xor_b32_e32 v226, v226, v227
	v_lshlrev_b32_e32 v226, 6, v226
	v_and_b32_e32 v225, 1, v225
	v_lshl_or_b32 v226, v225, 5, v226
	v_lshl_add_u32 v226, v224, 7, v226
	v_add_u32_e32 v223, s78, v226
	v_and_b32_e32 v226, 63, v160
	v_lshrrev_b32_e32 v224, 5, v226
	v_bfe_u32 v227, v226, 2, 2
	v_lshl_add_u32 v224, v224, 2, v227
	v_lshlrev_b32_e32 v224, 7, v224
	v_bfe_u32 v227, v226, 3, 1
	v_lshl_or_b32 v224, v227, 6, v224
	v_bfe_u32 v227, v226, 4, 1
	v_lshl_or_b32 v224, v227, 5, v224
	v_and_b32_e32 v227, 3, v226
	v_lshl_or_b32 v224, v227, 3, v224
	v_add_u32_e32 v224, s78, v224
	v_xor_b32_e32 v225, 64, v224
	ds_write_b128 v223, v[36:39] offset:8192
	ds_write_b128 v223, v[32:35] offset:8208
	s_waitcnt lgkmcnt(0)
	s_barrier
	ds_read_b128 v[32:35], v107
	ds_read_b128 v[48:51], v107 offset:4096
	s_waitcnt lgkmcnt(1)
	v_mfma_f32_32x32x16_bf16 v[32:47], v[32:35], v[72:75], 0
	ds_read_b128 v[114:117], v108
	ds_read_b128 v[118:121], v108 offset:4096
	s_mov_b32 s6, 0x3e38aa3b
	s_mov_b32 s1, 0xf149f2ca
	v_add_u32_e32 v135, 0x2000, v111
	s_add_i32 s5, s5, 64
	s_cmpk_lg_i32 s5, 0x100
	s_waitcnt lgkmcnt(2)
	v_mfma_f32_32x32x16_bf16 v[48:63], v[48:51], v[72:75], 0
	s_waitcnt lgkmcnt(1)
	v_mfma_f32_32x32x16_bf16 v[32:47], v[114:117], v[64:67], v[32:47]
	ds_read_b128 v[114:117], v109 offset:4096
	s_waitcnt lgkmcnt(1)
	v_mfma_f32_32x32x16_bf16 v[48:63], v[118:121], v[64:67], v[48:63]
	s_waitcnt lgkmcnt(0)
	v_mfma_f32_32x32x16_bf16 v[48:63], v[114:117], v[68:71], v[48:63]
	ds_read_b128 v[114:117], v110 offset:4096
	s_waitcnt lgkmcnt(0)
	v_mfma_f32_32x32x16_bf16 v[48:63], v[114:117], v[76:79], v[48:63]
	ds_read_b128 v[114:117], v109
	ds_read_b128 v[118:121], v110
	s_waitcnt lgkmcnt(1)
	v_mfma_f32_32x32x16_bf16 v[32:47], v[114:117], v[68:71], v[32:47]
	s_nop 7
	s_nop 0
	s_nop 0
	s_nop 0
	s_nop 0
	s_nop 0
	s_nop 0
	s_nop 0
	s_nop 0
	s_nop 0
	s_nop 0
	s_waitcnt lgkmcnt(0)
	v_mfma_f32_32x32x16_bf16 v[32:47], v[118:121], v[76:79], v[32:47]
	s_nop 0
	s_nop 0
	s_nop 9
	v_mov_b32_e32 v114, v32
	v_mov_b32_e32 v115, v33
	s_nop 0
	v_max3_f32 v32, v114, s1, v115
	s_nop 0
	v_max3_f32 v32, v32, v34, v35
	s_nop 0
	v_max3_f32 v32, v32, v36, v37
	s_nop 0
	v_max3_f32 v32, v32, v38, v39
	s_nop 0
	v_max3_f32 v32, v32, v40, v41
	s_nop 0
	v_max3_f32 v32, v32, v42, v43
	s_nop 0
	v_max3_f32 v32, v32, v44, v45
	v_max3_f32 v32, v32, v46, v47
	v_max3_f32 v32, v32, v48, v49
	v_max3_f32 v32, v32, v50, v51
	v_max3_f32 v32, v32, v52, v53
	v_max3_f32 v32, v32, v54, v55
	v_max3_f32 v32, v32, v56, v57
	v_max3_f32 v32, v32, v58, v59
	v_max3_f32 v32, v32, v60, v61
	v_max3_f32 v32, v32, v62, v63
	ds_bpermute_b32 v33, v100, v32
	s_waitcnt lgkmcnt(0)
	v_max3_f32 v33, v112, v32, v33
	v_mul_f32_e32 v229, 0xbe38aa3b, v33
	v_fma_f32 v113, v115, s6, v229
	v_fma_f32 v32, v112, s6, v229
	v_fma_f32 v112, v114, s6, v229
	s_nop 0
	v_exp_f32_e32 v113, v113
	s_nop 0
	v_fma_f32 v116, v35, s6, v229
	v_exp_f32_e32 v112, v112
	v_fma_f32 v115, v34, s6, v229
	s_nop 0
	v_exp_f32_e32 v116, v116
	s_nop 0
	v_exp_f32_e32 v115, v115
	s_nop 0
	s_nop 0
	v_exp_f32_e32 v32, v32
	s_nop 0
	v_add_f32_e32 v114, 0, v112
	v_add_f32_e32 v114, v113, v114
	s_nop 0
	v_fma_f32 v35, v36, s6, v229
	s_nop 0
	s_nop 0
	v_add_f32_e32 v34, v115, v114
	v_fma_f32 v114, v37, s6, v229
	s_nop 0
	v_exp_f32_e32 v114, v114
	v_exp_f32_e32 v35, v35
	v_add_f32_e32 v34, v116, v34
	v_pk_mul_f32 v[30:31], v[30:31], v[32:33] op_sel_hi:[1,0]
	s_nop 0
	v_fma_f32 v36, v39, s6, v229
	s_nop 0
	v_mov_b32_e32 v117, v35
	v_fma_f32 v35, v38, s6, v229
	v_exp_f32_e32 v36, v36
	s_nop 0
	v_exp_f32_e32 v35, v35
	v_add_f32_e32 v34, v117, v34
	v_add_f32_e32 v34, v114, v34
	v_mov_b32_e32 v118, v36
	v_fma_f32 v36, v41, s6, v229
	s_nop 0
	v_mov_b32_e32 v119, v35
	v_fma_f32 v35, v40, s6, v229
	v_exp_f32_e32 v36, v36
	s_nop 0
	v_exp_f32_e32 v35, v35
	v_add_f32_e32 v34, v119, v34
	v_add_f32_e32 v34, v118, v34
	v_mov_b32_e32 v120, v36
	v_fma_f32 v36, v43, s6, v229
	s_nop 0
	v_mov_b32_e32 v121, v35
	v_fma_f32 v35, v42, s6, v229
	v_exp_f32_e32 v36, v36
	s_nop 0
	v_exp_f32_e32 v35, v35
	v_add_f32_e32 v34, v121, v34
	v_add_f32_e32 v34, v120, v34
	v_mov_b32_e32 v122, v36
	v_fma_f32 v36, v45, s6, v229
	s_nop 0
	v_mov_b32_e32 v123, v35
	v_fma_f32 v35, v44, s6, v229
	v_exp_f32_e32 v36, v36
	s_nop 0
	v_exp_f32_e32 v35, v35
	v_add_f32_e32 v34, v123, v34
	v_add_f32_e32 v34, v122, v34
	v_mov_b32_e32 v124, v36
	v_fma_f32 v36, v47, s6, v229
	s_nop 0
	v_mov_b32_e32 v125, v35
	v_fma_f32 v35, v46, s6, v229
	v_exp_f32_e32 v36, v36
	s_nop 0
	v_exp_f32_e32 v35, v35
	v_add_f32_e32 v34, v125, v34
	v_add_f32_e32 v34, v124, v34
	v_mov_b32_e32 v47, v36
	v_fma_f32 v36, v49, s6, v229
	s_nop 0
	v_mov_b32_e32 v46, v35
	v_fma_f32 v35, v48, s6, v229
	v_exp_f32_e32 v36, v36
	s_nop 0
	v_exp_f32_e32 v35, v35
	v_add_f32_e32 v34, v46, v34
	v_add_f32_e32 v34, v47, v34
	v_mov_b32_e32 v49, v36
	v_fma_f32 v36, v51, s6, v229
	s_nop 0
	v_mov_b32_e32 v48, v35
	v_fma_f32 v35, v50, s6, v229
	v_exp_f32_e32 v36, v36
	s_nop 0
	v_exp_f32_e32 v35, v35
	v_add_f32_e32 v34, v48, v34
	v_add_f32_e32 v34, v49, v34
	v_mov_b32_e32 v51, v36
	v_fma_f32 v36, v53, s6, v229
	s_nop 0
	v_mov_b32_e32 v50, v35
	v_fma_f32 v35, v52, s6, v229
	v_exp_f32_e32 v36, v36
	s_nop 0
	v_exp_f32_e32 v35, v35
	v_add_f32_e32 v34, v50, v34
	v_add_f32_e32 v34, v51, v34
	v_mov_b32_e32 v53, v36
	v_fma_f32 v36, v55, s6, v229
	s_nop 0
	v_mov_b32_e32 v52, v35
	v_fma_f32 v35, v54, s6, v229
	v_exp_f32_e32 v36, v36
	s_nop 0
	v_exp_f32_e32 v35, v35
	v_add_f32_e32 v34, v52, v34
	v_add_f32_e32 v34, v53, v34
	v_mov_b32_e32 v55, v36
	v_fma_f32 v36, v57, s6, v229
	s_nop 0
	v_mov_b32_e32 v54, v35
	v_fma_f32 v35, v56, s6, v229
	v_exp_f32_e32 v36, v36
	s_nop 0
	v_exp_f32_e32 v35, v35
	v_add_f32_e32 v34, v54, v34
	v_add_f32_e32 v34, v55, v34
	v_mov_b32_e32 v57, v36
	v_fma_f32 v36, v59, s6, v229
	s_nop 0
	v_mov_b32_e32 v56, v35
	v_fma_f32 v35, v58, s6, v229
	v_exp_f32_e32 v36, v36
	s_nop 0
	v_exp_f32_e32 v35, v35
	v_add_f32_e32 v34, v56, v34
	v_add_f32_e32 v34, v57, v34
	v_mov_b32_e32 v59, v36
	v_cvt_pk_bf16_f32 v38, v112, v113
	v_add_u32_e32 v112, 0x3000, v111
	v_mov_b32_e32 v58, v35
	v_add_f32_e32 v34, v58, v34
	v_add_f32_e32 v126, v59, v34
	v_fma_f32 v34, v60, s6, v229
	v_mov_b32_e32 v127, v34
	ds_read_b64_tr_b16 v[34:35], v224 offset:8192
	ds_read_b64_tr_b16 v[36:37], v224 offset:9216
	ds_read_b64_tr_b16 v[42:43], v225 offset:8192
	ds_read_b64_tr_b16 v[44:45], v225 offset:9216
	v_pk_mul_f32 v[28:29], v[28:29], v[32:33] op_sel_hi:[1,0]
	v_pk_mul_f32 v[26:27], v[26:27], v[32:33] op_sel_hi:[1,0]
	v_pk_mul_f32 v[24:25], v[24:25], v[32:33] op_sel_hi:[1,0]
	v_pk_mul_f32 v[22:23], v[22:23], v[32:33] op_sel_hi:[1,0]
	v_pk_mul_f32 v[20:21], v[20:21], v[32:33] op_sel_hi:[1,0]
	v_pk_mul_f32 v[18:19], v[18:19], v[32:33] op_sel_hi:[1,0]
	v_pk_mul_f32 v[16:17], v[16:17], v[32:33] op_sel_hi:[1,0]
	v_cvt_pk_bf16_f32 v39, v115, v116
	v_cvt_pk_bf16_f32 v40, v117, v114
	v_cvt_pk_bf16_f32 v41, v119, v118
	v_fma_f32 v134, v61, s6, v229
	v_pk_mul_f32 v[14:15], v[14:15], v[32:33] op_sel_hi:[1,0]
	s_waitcnt lgkmcnt(2)
	v_mfma_f32_32x32x16_bf16 v[16:31], v[34:37], v[38:41], v[16:31]
	ds_read_b64_tr_b16 v[34:35], v224 offset:10240
	ds_read_b64_tr_b16 v[36:37], v224 offset:11264
	v_mul_f32_e64 v12, v12, v32
	v_mul_f32_e64 v13, v13, v32
	v_mul_f32_e64 v10, v10, v32
	v_mul_f32_e64 v11, v11, v32
	v_pk_mul_f32 v[8:9], v[8:9], v[32:33] op_sel_hi:[1,0]
	v_pk_mul_f32 v[6:7], v[6:7], v[32:33] op_sel_hi:[1,0]
	v_pk_mul_f32 v[4:5], v[4:5], v[32:33] op_sel_hi:[1,0]
	v_pk_mul_f32 v[2:3], v[2:3], v[32:33] op_sel_hi:[1,0]
	v_pk_mul_f32 v[0:1], v[0:1], v[32:33] op_sel_hi:[1,0]
	v_fma_f32 v61, v62, s6, v229
	s_waitcnt lgkmcnt(2)
	v_mfma_f32_32x32x16_bf16 v[0:15], v[42:45], v[38:41], v[0:15]
	v_mov_b32_e32 v38, v134
	v_exp_f32_e32 v113, v38
	v_cvt_pk_bf16_f32 v38, v121, v120
	v_cvt_pk_bf16_f32 v39, v123, v122
	v_cvt_pk_bf16_f32 v40, v125, v124
	v_cvt_pk_bf16_f32 v41, v46, v47
	ds_read_b64_tr_b16 v[42:43], v225 offset:10240
	ds_read_b64_tr_b16 v[44:45], v225 offset:11264
	v_mov_b32_e32 v46, v113
	s_waitcnt lgkmcnt(2)
	v_mfma_f32_32x32x16_bf16 v[16:31], v[34:37], v[38:41], v[16:31]
	v_exp_f32_e32 v34, v127
	s_nop 1
	v_mov_b32_e32 v47, v34
	ds_read_b64_tr_b16 v[34:35], v224 offset:12288
	ds_read_b64_tr_b16 v[36:37], v224 offset:13312
	s_waitcnt lgkmcnt(2)
	v_mfma_f32_32x32x16_bf16 v[0:15], v[42:45], v[38:41], v[0:15]
	ds_read_b64_tr_b16 v[42:43], v225 offset:12288
	ds_read_b64_tr_b16 v[44:45], v225 offset:13312
	v_cvt_pk_bf16_f32 v38, v48, v49
	v_cvt_pk_bf16_f32 v39, v50, v51
	v_cvt_pk_bf16_f32 v40, v52, v53
	v_cvt_pk_bf16_f32 v41, v54, v55
	v_add_f32_e32 v60, v47, v126
	v_add_f32_e32 v60, v46, v60
	s_waitcnt lgkmcnt(2)
	v_mfma_f32_32x32x16_bf16 v[16:31], v[34:37], v[38:41], v[16:31]
	v_fma_f32 v34, v63, s6, v229
	s_nop 0
	v_exp_f32_e32 v34, v34
	v_mov_b32_e32 v35, v61
	v_exp_f32_e32 v48, v35
	v_mov_b32_e32 v49, v34
	s_waitcnt lgkmcnt(0)
	v_mfma_f32_32x32x16_bf16 v[0:15], v[42:45], v[38:41], v[0:15]
	ds_read_b64_tr_b16 v[34:35], v224 offset:14336
	ds_read_b64_tr_b16 v[36:37], v224 offset:15360
	ds_read_b64_tr_b16 v[42:43], v225 offset:14336
	ds_read_b64_tr_b16 v[44:45], v225 offset:15360
	v_cvt_pk_bf16_f32 v38, v56, v57
	v_cvt_pk_bf16_f32 v39, v58, v59
	v_mov_b32_e32 v41, v48
	v_add_f32_e32 v48, v41, v60
	v_cvt_pk_bf16_f32 v40, v47, v46
	v_cvt_pk_bf16_f32 v41, v41, v49
	s_waitcnt lgkmcnt(2)
	s_nop 0
	v_mfma_f32_32x32x16_bf16 v[16:31], v[34:37], v[38:41], v[16:31]
	v_add_f32_e32 v34, v49, v48
	ds_bpermute_b32 v35, v100, v34
	s_waitcnt lgkmcnt(0)
	v_add_f32_e32 v34, v34, v35
	v_mfma_f32_32x32x16_bf16 v[0:15], v[42:45], v[38:41], v[0:15]
	v_fmac_f32_e32 v34, v105, v32
	s_cbranch_scc1 .LBB0_237
	v_mul_f32_e32 v33, 0x3e000000, v33
	v_max_f32_e32 v32, v99, v99
	v_max_f32_e32 v35, v33, v33
	v_max_f32_e32 v32, v35, v32
	v_sub_f32_e32 v33, v33, v32
	v_sub_f32_e32 v32, v99, v32
	v_mul_f32_e32 v33, 0x3fb8aa3b, v33
	v_mul_f32_e32 v32, 0x3fb8aa3b, v32
	v_exp_f32_e32 v33, v33
	v_exp_f32_e32 v32, v32
	s_lshl_b32 s92, s4, 1
	v_lshlrev_b32_e32 v128, 3, v98
	v_fmac_f32_e32 v32, v33, v34
	v_div_scale_f32 v34, s[0:1], v32, v32, v33
	v_rcp_f32_e32 v35, v34
	v_readlane_b32 s0, v254, 43
	v_readlane_b32 s1, v254, 44
	v_fma_f32 v36, -v34, v35, 1.0
	v_fmac_f32_e32 v35, v36, v35
	v_div_scale_f32 v36, vcc, v33, v32, v33
	v_mul_f32_e32 v37, v36, v35
	v_fma_f32 v38, -v34, v37, v36
	v_fmac_f32_e32 v37, v38, v35
	v_fma_f32 v34, -v34, v37, v36
	v_div_fmas_f32 v34, v34, v35, v37
	v_div_fixup_f32 v32, v34, v32, v33
	v_lshlrev_b64 v[34:35], 11, v[96:97]
	v_lshl_add_u64 v[34:35], s[0:1], 0, v[34:35]
	v_lshl_add_u64 v[34:35], v[34:35], 0, s[92:93]
	v_pk_mul_f32 v[16:17], v[16:17], v[32:33] op_sel_hi:[1,0]
	v_pk_mul_f32 v[18:19], v[18:19], v[32:33] op_sel_hi:[1,0]
	v_cvt_pk_bf16_f32 v16, v16, v17
	v_cvt_pk_bf16_f32 v17, v18, v19
	v_lshl_add_u64 v[18:19], v[34:35], 0, v[128:129]
	s_mov_b64 s[0:1], 0x153ca600
	v_lshl_add_u64 v[34:35], v[18:19], 0, s[0:1]
	s_mov_b32 s0, 0x153ca000
	v_add_co_u32_e32 v18, vcc, s0, v18
	v_pk_mul_f32 v[0:1], v[0:1], v[32:33] op_sel_hi:[1,0]
	v_pk_mul_f32 v[2:3], v[2:3], v[32:33] op_sel_hi:[1,0]
	v_addc_co_u32_e32 v19, vcc, 0, v19, vcc
	v_cvt_pk_bf16_f32 v0, v0, v1
	v_cvt_pk_bf16_f32 v1, v2, v3
	global_store_dwordx2 v[18:19], v[16:17], off offset:1536
	v_pk_mul_f32 v[16:17], v[20:21], v[32:33] op_sel_hi:[1,0]
	v_pk_mul_f32 v[18:19], v[22:23], v[32:33] op_sel_hi:[1,0]
	global_store_dwordx2 v[34:35], v[0:1], off offset:64
	v_pk_mul_f32 v[0:1], v[4:5], v[32:33] op_sel_hi:[1,0]
	v_pk_mul_f32 v[2:3], v[6:7], v[32:33] op_sel_hi:[1,0]
	v_cvt_pk_bf16_f32 v16, v16, v17
	v_cvt_pk_bf16_f32 v17, v18, v19
	v_cvt_pk_bf16_f32 v0, v0, v1
	v_cvt_pk_bf16_f32 v1, v2, v3
	global_store_dwordx2 v[34:35], v[16:17], off offset:16
	v_pk_mul_f32 v[16:17], v[24:25], v[32:33] op_sel_hi:[1,0]
	v_pk_mul_f32 v[18:19], v[26:27], v[32:33] op_sel_hi:[1,0]
	global_store_dwordx2 v[34:35], v[0:1], off offset:80
	v_pk_mul_f32 v[0:1], v[8:9], v[32:33] op_sel_hi:[1,0]
	v_pk_mul_f32 v[2:3], v[10:11], v[32:33] op_sel_hi:[1,0]
	v_cvt_pk_bf16_f32 v16, v16, v17
	v_cvt_pk_bf16_f32 v17, v18, v19
	v_cvt_pk_bf16_f32 v0, v0, v1
	v_cvt_pk_bf16_f32 v1, v2, v3
	global_store_dwordx2 v[34:35], v[16:17], off offset:32
	v_pk_mul_f32 v[16:17], v[28:29], v[32:33] op_sel_hi:[1,0]
	v_pk_mul_f32 v[18:19], v[30:31], v[32:33] op_sel_hi:[1,0]
	global_store_dwordx2 v[34:35], v[0:1], off offset:96
	v_pk_mul_f32 v[0:1], v[12:13], v[32:33] op_sel_hi:[1,0]
	v_pk_mul_f32 v[2:3], v[14:15], v[32:33] op_sel_hi:[1,0]
	v_cvt_pk_bf16_f32 v16, v16, v17
	v_cvt_pk_bf16_f32 v17, v18, v19
	v_cvt_pk_bf16_f32 v0, v0, v1
	v_cvt_pk_bf16_f32 v1, v2, v3
	global_store_dwordx2 v[34:35], v[16:17], off offset:48
	global_store_dwordx2 v[34:35], v[0:1], off offset:112
	s_barrier
	s_mov_b64 s[0:1], 0

.LBB0_245:
	s_barrier
	ds_write_b128 v104, v[44:47]
	ds_write_b128 v105, v[40:43]
	v_and_b32_e32 v223, 0xff, v160
	v_lshrrev_b32_e32 v224, 2, v223
	v_and_b32_e32 v225, 3, v223
	v_lshrrev_b32_e32 v226, 1, v225
	v_bfe_u32 v227, v224, 1, 1
	v_xor_b32_e32 v226, v226, v227
	v_lshlrev_b32_e32 v226, 6, v226
	v_and_b32_e32 v225, 1, v225
	v_lshl_or_b32 v226, v225, 5, v226
	v_lshl_add_u32 v226, v224, 7, v226
	v_add_u32_e32 v223, s78, v226
	v_and_b32_e32 v226, 63, v160
	v_lshrrev_b32_e32 v224, 5, v226
	v_bfe_u32 v227, v226, 2, 2
	v_lshl_add_u32 v224, v224, 2, v227
	v_lshlrev_b32_e32 v224, 7, v224
	v_bfe_u32 v227, v226, 3, 1
	v_lshl_or_b32 v224, v227, 6, v224
	v_bfe_u32 v227, v226, 4, 1
	v_lshl_or_b32 v224, v227, 5, v224
	v_and_b32_e32 v227, 3, v226
	v_lshl_or_b32 v224, v227, 3, v224
	v_add_u32_e32 v224, s78, v224
	v_xor_b32_e32 v225, 64, v224
	ds_write_b128 v223, v[36:39] offset:8192
	ds_write_b128 v223, v[32:35] offset:8208
	s_waitcnt lgkmcnt(0)
	s_barrier
	ds_read_b128 v[32:35], v106
	ds_read_b128 v[48:51], v106 offset:4096
	s_waitcnt lgkmcnt(1)
	v_mfma_f32_32x32x16_bf16 v[32:47], v[32:35], v[64:67], 0
	ds_read_b128 v[114:117], v108
	ds_read_b128 v[118:121], v108 offset:4096
	s_mov_b32 s6, 0x3e38aa3b
	s_mov_b32 s5, 0xf149f2ca
	v_add_u32_e32 v134, 0x2000, v111
	s_add_u32 s0, s0, 0x74000
	s_addc_u32 s1, s1, 0
	s_cmp_lg_u32 s0, 0x1d0000
	s_waitcnt lgkmcnt(2)
	v_mfma_f32_32x32x16_bf16 v[48:63], v[48:51], v[64:67], 0
	s_waitcnt lgkmcnt(1)
	v_mfma_f32_32x32x16_bf16 v[32:47], v[114:117], v[68:71], v[32:47]
	ds_read_b128 v[114:117], v109 offset:4096
	s_waitcnt lgkmcnt(1)
	v_mfma_f32_32x32x16_bf16 v[48:63], v[118:121], v[68:71], v[48:63]
	s_waitcnt lgkmcnt(0)
	v_mfma_f32_32x32x16_bf16 v[48:63], v[114:117], v[72:75], v[48:63]
	ds_read_b128 v[114:117], v110 offset:4096
	s_waitcnt lgkmcnt(0)
	v_mfma_f32_32x32x16_bf16 v[48:63], v[114:117], v[76:79], v[48:63]
	ds_read_b128 v[114:117], v109
	ds_read_b128 v[118:121], v110
	s_waitcnt lgkmcnt(1)
	v_mfma_f32_32x32x16_bf16 v[32:47], v[114:117], v[72:75], v[32:47]
	s_nop 7
	s_nop 0
	s_nop 0
	s_nop 0
	s_nop 0
	s_nop 0
	s_nop 0
	s_nop 0
	s_nop 0
	s_nop 0
	s_nop 0
	s_waitcnt lgkmcnt(0)
	v_mfma_f32_32x32x16_bf16 v[32:47], v[118:121], v[76:79], v[32:47]
	s_nop 0
	s_nop 0
	s_nop 9
	v_mov_b32_e32 v114, v32
	v_mov_b32_e32 v115, v33
	s_nop 0
	v_max3_f32 v32, v114, s5, v115
	s_nop 0
	v_max3_f32 v32, v32, v34, v35
	s_nop 0
	v_max3_f32 v32, v32, v36, v37
	s_nop 0
	v_max3_f32 v32, v32, v38, v39
	s_nop 0
	v_max3_f32 v32, v32, v40, v41
	s_nop 0
	v_max3_f32 v32, v32, v42, v43
	s_nop 0
	v_max3_f32 v32, v32, v44, v45
	v_max3_f32 v32, v32, v46, v47
	v_max3_f32 v32, v32, v48, v49
	v_max3_f32 v32, v32, v50, v51
	v_max3_f32 v32, v32, v52, v53
	v_max3_f32 v32, v32, v54, v55
	v_max3_f32 v32, v32, v56, v57
	v_max3_f32 v32, v32, v58, v59
	v_max3_f32 v32, v32, v60, v61
	v_max3_f32 v32, v32, v62, v63
	ds_bpermute_b32 v33, v101, v32
	s_waitcnt lgkmcnt(0)
	v_max3_f32 v33, v112, v32, v33
	v_mul_f32_e32 v229, 0xbe38aa3b, v33
	v_fma_f32 v113, v115, s6, v229
	v_fma_f32 v32, v112, s6, v229
	v_fma_f32 v112, v114, s6, v229
	s_nop 0
	v_exp_f32_e32 v113, v113
	s_nop 0
	v_fma_f32 v116, v35, s6, v229
	v_exp_f32_e32 v112, v112
	v_fma_f32 v115, v34, s6, v229
	s_nop 0
	v_exp_f32_e32 v116, v116
	s_nop 0
	v_exp_f32_e32 v115, v115
	s_nop 0
	s_nop 0
	v_exp_f32_e32 v32, v32
	s_nop 0
	v_add_f32_e32 v114, 0, v112
	v_add_f32_e32 v114, v113, v114
	s_nop 0
	v_fma_f32 v35, v36, s6, v229
	s_nop 0
	s_nop 0
	v_add_f32_e32 v34, v115, v114
	v_fma_f32 v114, v37, s6, v229
	s_nop 0
	v_exp_f32_e32 v114, v114
	v_exp_f32_e32 v35, v35
	v_add_f32_e32 v34, v116, v34
	v_pk_mul_f32 v[30:31], v[30:31], v[32:33] op_sel_hi:[1,0]
	s_nop 0
	v_fma_f32 v36, v39, s6, v229
	s_nop 0
	v_mov_b32_e32 v117, v35
	v_fma_f32 v35, v38, s6, v229
	v_exp_f32_e32 v36, v36
	s_nop 0
	v_exp_f32_e32 v35, v35
	v_add_f32_e32 v34, v117, v34
	v_add_f32_e32 v34, v114, v34
	v_mov_b32_e32 v118, v36
	v_fma_f32 v36, v41, s6, v229
	s_nop 0
	v_mov_b32_e32 v119, v35
	v_fma_f32 v35, v40, s6, v229
	v_exp_f32_e32 v36, v36
	s_nop 0
	v_exp_f32_e32 v35, v35
	v_add_f32_e32 v34, v119, v34
	v_add_f32_e32 v34, v118, v34
	v_mov_b32_e32 v120, v36
	v_fma_f32 v36, v43, s6, v229
	s_nop 0
	v_mov_b32_e32 v121, v35
	v_fma_f32 v35, v42, s6, v229
	v_exp_f32_e32 v36, v36
	s_nop 0
	v_exp_f32_e32 v35, v35
	v_add_f32_e32 v34, v121, v34
	v_add_f32_e32 v34, v120, v34
	v_mov_b32_e32 v122, v36
	v_fma_f32 v36, v45, s6, v229
	s_nop 0
	v_mov_b32_e32 v123, v35
	v_fma_f32 v35, v44, s6, v229
	v_exp_f32_e32 v36, v36
	s_nop 0
	v_exp_f32_e32 v35, v35
	v_add_f32_e32 v34, v123, v34
	v_add_f32_e32 v34, v122, v34
	v_mov_b32_e32 v124, v36
	v_fma_f32 v36, v47, s6, v229
	s_nop 0
	v_mov_b32_e32 v125, v35
	v_fma_f32 v35, v46, s6, v229
	v_exp_f32_e32 v36, v36
	s_nop 0
	v_exp_f32_e32 v35, v35
	v_add_f32_e32 v34, v125, v34
	v_add_f32_e32 v34, v124, v34
	v_mov_b32_e32 v47, v36
	v_fma_f32 v36, v49, s6, v229
	s_nop 0
	v_mov_b32_e32 v46, v35
	v_fma_f32 v35, v48, s6, v229
	v_exp_f32_e32 v36, v36
	s_nop 0
	v_exp_f32_e32 v35, v35
	v_add_f32_e32 v34, v46, v34
	v_add_f32_e32 v34, v47, v34
	v_mov_b32_e32 v49, v36
	v_fma_f32 v36, v51, s6, v229
	s_nop 0
	v_mov_b32_e32 v48, v35
	v_fma_f32 v35, v50, s6, v229
	v_exp_f32_e32 v36, v36
	s_nop 0
	v_exp_f32_e32 v35, v35
	v_add_f32_e32 v34, v48, v34
	v_add_f32_e32 v34, v49, v34
	v_mov_b32_e32 v51, v36
	v_fma_f32 v36, v53, s6, v229
	s_nop 0
	v_mov_b32_e32 v50, v35
	v_fma_f32 v35, v52, s6, v229
	v_exp_f32_e32 v36, v36
	s_nop 0
	v_exp_f32_e32 v35, v35
	v_add_f32_e32 v34, v50, v34
	v_add_f32_e32 v34, v51, v34
	v_mov_b32_e32 v53, v36
	v_fma_f32 v36, v55, s6, v229
	s_nop 0
	v_mov_b32_e32 v52, v35
	v_fma_f32 v35, v54, s6, v229
	v_exp_f32_e32 v36, v36
	s_nop 0
	v_exp_f32_e32 v35, v35
	v_add_f32_e32 v34, v52, v34
	v_add_f32_e32 v34, v53, v34
	v_mov_b32_e32 v55, v36
	v_fma_f32 v36, v57, s6, v229
	s_nop 0
	v_mov_b32_e32 v54, v35
	v_fma_f32 v35, v56, s6, v229
	v_exp_f32_e32 v36, v36
	s_nop 0
	v_exp_f32_e32 v35, v35
	v_add_f32_e32 v34, v54, v34
	v_add_f32_e32 v34, v55, v34
	v_mov_b32_e32 v57, v36
	v_fma_f32 v36, v59, s6, v229
	s_nop 0
	v_mov_b32_e32 v56, v35
	v_fma_f32 v35, v58, s6, v229
	v_exp_f32_e32 v36, v36
	s_nop 0
	v_exp_f32_e32 v35, v35
	v_add_f32_e32 v34, v56, v34
	v_add_f32_e32 v34, v57, v34
	v_mov_b32_e32 v59, v36
	v_cvt_pk_bf16_f32 v38, v112, v113
	v_add_u32_e32 v112, 0x3000, v111
	v_mov_b32_e32 v58, v35
	v_add_f32_e32 v34, v58, v34
	v_add_f32_e32 v126, v59, v34
	v_fma_f32 v34, v60, s6, v229
	v_mov_b32_e32 v127, v34
	ds_read_b64_tr_b16 v[34:35], v224 offset:8192
	ds_read_b64_tr_b16 v[36:37], v224 offset:9216
	ds_read_b64_tr_b16 v[42:43], v225 offset:8192
	ds_read_b64_tr_b16 v[44:45], v225 offset:9216
	v_pk_mul_f32 v[28:29], v[28:29], v[32:33] op_sel_hi:[1,0]
	v_pk_mul_f32 v[26:27], v[26:27], v[32:33] op_sel_hi:[1,0]
	v_pk_mul_f32 v[24:25], v[24:25], v[32:33] op_sel_hi:[1,0]
	v_pk_mul_f32 v[22:23], v[22:23], v[32:33] op_sel_hi:[1,0]
	v_pk_mul_f32 v[20:21], v[20:21], v[32:33] op_sel_hi:[1,0]
	v_pk_mul_f32 v[18:19], v[18:19], v[32:33] op_sel_hi:[1,0]
	v_pk_mul_f32 v[16:17], v[16:17], v[32:33] op_sel_hi:[1,0]
	v_cvt_pk_bf16_f32 v39, v115, v116
	v_cvt_pk_bf16_f32 v40, v117, v114
	v_cvt_pk_bf16_f32 v41, v119, v118
	v_fma_f32 v128, v61, s6, v229
	v_pk_mul_f32 v[14:15], v[14:15], v[32:33] op_sel_hi:[1,0]
	s_waitcnt lgkmcnt(2)
	v_mfma_f32_32x32x16_bf16 v[16:31], v[34:37], v[38:41], v[16:31]
	ds_read_b64_tr_b16 v[34:35], v224 offset:10240
	ds_read_b64_tr_b16 v[36:37], v224 offset:11264
	v_mul_f32_e64 v12, v12, v32
	v_mul_f32_e64 v13, v13, v32
	v_mul_f32_e64 v10, v10, v32
	v_mul_f32_e64 v11, v11, v32
	v_pk_mul_f32 v[8:9], v[8:9], v[32:33] op_sel_hi:[1,0]
	v_pk_mul_f32 v[6:7], v[6:7], v[32:33] op_sel_hi:[1,0]
	v_pk_mul_f32 v[4:5], v[4:5], v[32:33] op_sel_hi:[1,0]
	v_pk_mul_f32 v[2:3], v[2:3], v[32:33] op_sel_hi:[1,0]
	v_pk_mul_f32 v[0:1], v[0:1], v[32:33] op_sel_hi:[1,0]
	v_fma_f32 v61, v62, s6, v229
	s_waitcnt lgkmcnt(2)
	v_mfma_f32_32x32x16_bf16 v[0:15], v[42:45], v[38:41], v[0:15]
	v_mov_b32_e32 v38, v128
	v_exp_f32_e32 v113, v38
	v_cvt_pk_bf16_f32 v38, v121, v120
	v_cvt_pk_bf16_f32 v39, v123, v122
	v_cvt_pk_bf16_f32 v40, v125, v124
	v_cvt_pk_bf16_f32 v41, v46, v47
	ds_read_b64_tr_b16 v[42:43], v225 offset:10240
	ds_read_b64_tr_b16 v[44:45], v225 offset:11264
	v_mov_b32_e32 v46, v113
	s_waitcnt lgkmcnt(2)
	v_mfma_f32_32x32x16_bf16 v[16:31], v[34:37], v[38:41], v[16:31]
	v_exp_f32_e32 v34, v127
	s_nop 1
	v_mov_b32_e32 v47, v34
	ds_read_b64_tr_b16 v[34:35], v224 offset:12288
	ds_read_b64_tr_b16 v[36:37], v224 offset:13312
	s_waitcnt lgkmcnt(2)
	v_mfma_f32_32x32x16_bf16 v[0:15], v[42:45], v[38:41], v[0:15]
	ds_read_b64_tr_b16 v[42:43], v225 offset:12288
	ds_read_b64_tr_b16 v[44:45], v225 offset:13312
	v_cvt_pk_bf16_f32 v38, v48, v49
	v_cvt_pk_bf16_f32 v39, v50, v51
	v_cvt_pk_bf16_f32 v40, v52, v53
	v_cvt_pk_bf16_f32 v41, v54, v55
	v_add_f32_e32 v60, v47, v126
	v_add_f32_e32 v60, v46, v60
	s_waitcnt lgkmcnt(2)
	v_mfma_f32_32x32x16_bf16 v[16:31], v[34:37], v[38:41], v[16:31]
	v_fma_f32 v34, v63, s6, v229
	s_nop 0
	v_exp_f32_e32 v34, v34
	v_mov_b32_e32 v35, v61
	v_exp_f32_e32 v48, v35
	v_mov_b32_e32 v49, v34
	s_waitcnt lgkmcnt(0)
	v_mfma_f32_32x32x16_bf16 v[0:15], v[42:45], v[38:41], v[0:15]
	ds_read_b64_tr_b16 v[34:35], v224 offset:14336
	ds_read_b64_tr_b16 v[36:37], v224 offset:15360
	ds_read_b64_tr_b16 v[42:43], v225 offset:14336
	ds_read_b64_tr_b16 v[44:45], v225 offset:15360
	v_cvt_pk_bf16_f32 v38, v56, v57
	v_cvt_pk_bf16_f32 v39, v58, v59
	v_mov_b32_e32 v41, v48
	v_add_f32_e32 v48, v41, v60
	v_cvt_pk_bf16_f32 v40, v47, v46
	v_cvt_pk_bf16_f32 v41, v41, v49
	s_waitcnt lgkmcnt(2)
	s_nop 0
	v_mfma_f32_32x32x16_bf16 v[16:31], v[34:37], v[38:41], v[16:31]
	v_add_f32_e32 v34, v49, v48
	ds_bpermute_b32 v35, v101, v34
	s_waitcnt lgkmcnt(0)
	v_add_f32_e32 v34, v34, v35
	v_mfma_f32_32x32x16_bf16 v[0:15], v[42:45], v[38:41], v[0:15]
	v_fmac_f32_e32 v34, v107, v32
	s_cbranch_scc1 .LBB0_243
	v_div_scale_f32 v32, s[0:1], v34, v34, 1.0
	v_rcp_f32_e32 v33, v32
	v_div_scale_f32 v35, vcc, 1.0, v34, 1.0
	v_readlane_b32 s0, v254, 43
	v_fma_f32 v36, -v32, v33, 1.0
	v_fmac_f32_e32 v33, v36, v33
	v_mul_f32_e32 v36, v35, v33
	v_fma_f32 v37, -v32, v36, v35
	v_fmac_f32_e32 v36, v37, v33
	v_fma_f32 v32, -v32, v36, v35
	v_div_fmas_f32 v32, v32, v33, v36
	v_div_fixup_f32 v32, v32, v34, 1.0
	v_lshlrev_b64 v[34:35], 11, v[96:97]
	v_readlane_b32 s1, v254, 44
	s_lshl_b32 s92, s4, 1
	v_pk_mul_f32 v[16:17], v[16:17], v[32:33] op_sel_hi:[1,0]
	v_lshl_add_u64 v[34:35], s[0:1], 0, v[34:35]
	v_lshl_add_u64 v[34:35], v[34:35], 0, s[92:93]
	v_pk_mul_f32 v[18:19], v[18:19], v[32:33] op_sel_hi:[1,0]
	v_lshlrev_b32_e32 v128, 3, v100
	v_cvt_pk_bf16_f32 v16, v16, v17
	v_cvt_pk_bf16_f32 v17, v18, v19
	v_lshl_add_u64 v[18:19], v[34:35], 0, v[128:129]
	s_mov_b64 s[0:1], 0x153ca200
	v_lshl_add_u64 v[34:35], v[18:19], 0, s[0:1]
	s_mov_b32 s0, 0x153ca000
	v_add_co_u32_e32 v18, vcc, s0, v18
	v_pk_mul_f32 v[0:1], v[0:1], v[32:33] op_sel_hi:[1,0]
	v_pk_mul_f32 v[2:3], v[2:3], v[32:33] op_sel_hi:[1,0]
	v_addc_co_u32_e32 v19, vcc, 0, v19, vcc
	v_cvt_pk_bf16_f32 v0, v0, v1
	v_cvt_pk_bf16_f32 v1, v2, v3
	global_store_dwordx2 v[18:19], v[16:17], off offset:512
	v_pk_mul_f32 v[16:17], v[20:21], v[32:33] op_sel_hi:[1,0]
	v_pk_mul_f32 v[18:19], v[22:23], v[32:33] op_sel_hi:[1,0]
	global_store_dwordx2 v[34:35], v[0:1], off offset:64
	v_pk_mul_f32 v[0:1], v[4:5], v[32:33] op_sel_hi:[1,0]
	v_pk_mul_f32 v[2:3], v[6:7], v[32:33] op_sel_hi:[1,0]
	v_cvt_pk_bf16_f32 v16, v16, v17
	v_cvt_pk_bf16_f32 v17, v18, v19
	v_cvt_pk_bf16_f32 v0, v0, v1
	v_cvt_pk_bf16_f32 v1, v2, v3
	global_store_dwordx2 v[34:35], v[16:17], off offset:16
	v_pk_mul_f32 v[16:17], v[24:25], v[32:33] op_sel_hi:[1,0]
	v_pk_mul_f32 v[18:19], v[26:27], v[32:33] op_sel_hi:[1,0]
	global_store_dwordx2 v[34:35], v[0:1], off offset:80
	v_pk_mul_f32 v[0:1], v[8:9], v[32:33] op_sel_hi:[1,0]
	v_pk_mul_f32 v[2:3], v[10:11], v[32:33] op_sel_hi:[1,0]
	v_cvt_pk_bf16_f32 v16, v16, v17
	v_cvt_pk_bf16_f32 v17, v18, v19
	v_cvt_pk_bf16_f32 v0, v0, v1
	v_cvt_pk_bf16_f32 v1, v2, v3
	global_store_dwordx2 v[34:35], v[16:17], off offset:32
	v_pk_mul_f32 v[16:17], v[28:29], v[32:33] op_sel_hi:[1,0]
	v_pk_mul_f32 v[18:19], v[30:31], v[32:33] op_sel_hi:[1,0]
	global_store_dwordx2 v[34:35], v[0:1], off offset:96
	v_pk_mul_f32 v[0:1], v[12:13], v[32:33] op_sel_hi:[1,0]
	v_pk_mul_f32 v[2:3], v[14:15], v[32:33] op_sel_hi:[1,0]
	v_cvt_pk_bf16_f32 v16, v16, v17
	v_cvt_pk_bf16_f32 v17, v18, v19
	v_cvt_pk_bf16_f32 v0, v0, v1
	v_cvt_pk_bf16_f32 v1, v2, v3
	global_store_dwordx2 v[34:35], v[16:17], off offset:48
	global_store_dwordx2 v[34:35], v[0:1], off offset:112
	s_barrier
